# RNN unit set-up: conv bias and both conv-weight loads in flight together, one per-lane-selected load for the three gate parameter rows, tile-0 x loads waited once (4 fewer serialized global round trip
# speedup vs baseline: 1.0096x; 1.0010x over previous
.LBB0_85:
	v_mov_b32_e32 v182, v186
	s_and_b32 s23, s22, 7
	s_movk_i32 s0, 0x80
	s_lshl_b32 s6, s23, 7
	v_cmp_gt_i32_e32 vcc, s0, v182
	v_lshl_add_u32 v116, v182, 2, 0
	s_and_saveexec_b64 s[0:1], vcc
	s_cbranch_execz .LBB0_87
	s_lshl_b32 s7, s6, 2
	s_add_u32 s10, s34, s7
	s_addc_u32 s11, s35, 0
	v_ashrrev_i32_e32 v183, 31, v182
	v_lshl_add_u64 v[2:3], v[182:183], 2, s[10:11]
	global_load_dword v12, v[2:3], off
	v_add_u32_e32 v13, 0x19c00, v116
.LBB0_87:
	s_or_b64 exec, exec, s[0:1]
	v_bfe_u32 v0, v182, 6, 1
	v_bfe_u32 v2, v182, 3, 1
	v_cmp_eq_u32_e64 s[42:43], v2, v0
	v_lshlrev_b32_e32 v0, 6, v182
	v_and_b32_e32 v141, 15, v182
	v_and_b32_e32 v0, 0xc00, v0
	v_lshlrev_b32_e32 v117, 4, v182
	v_bfe_u32 v3, v182, 1, 2
	v_and_b32_e32 v10, 16, v117
	v_mov_b32_e32 v2, 0
	v_cmp_eq_u32_e32 vcc, 0, v3
	v_cmp_eq_u32_e64 s[0:1], 1, v3
	v_cmp_eq_u32_e64 s[38:39], 2, v3
	v_cmp_eq_u32_e64 s[40:41], 3, v3
	v_lshlrev_b32_e32 v0, 2, v0
	v_lshlrev_b32_e32 v8, 2, v141
	v_mov_b32_e32 v4, 0
	v_mov_b32_e32 v5, 0
	v_mov_b32_e32 v6, 0
	v_mov_b32_e32 v7, 0
	s_and_saveexec_b64 s[10:11], s[42:43]
	s_cbranch_execz .LBB0_89
	v_ashrrev_i32_e32 v3, 3, v182
	v_and_b32_e32 v4, -16, v3
	v_lshl_add_u64 v[6:7], s[18:19], 0, v[0:1]
	s_lshl_b32 s56, s6, 2
	v_ashrrev_i32_e32 v5, 31, v4
	v_lshl_add_u64 v[6:7], v[6:7], 0, s[56:57]
	v_lshl_add_u64 v[4:5], v[4:5], 2, v[6:7]
	v_mov_b32_e32 v9, v1
	v_lshl_add_u64 v[4:5], v[4:5], 0, v[8:9]
	global_load_dword v3, v[4:5], off
	global_load_dword v11, v[4:5], off offset:256
	s_waitcnt vmcnt(0)
	v_cvt_pk_bf16_f32 v3, v3, v1
	s_nop 0
	v_lshlrev_b32_sdwa v3, v10, v3 dst_sel:DWORD dst_unused:UNUSED_PAD src0_sel:DWORD src1_sel:WORD_0
	v_cndmask_b32_e32 v4, 0, v3, vcc
	v_cndmask_b32_e64 v5, 0, v3, s[0:1]
	v_cndmask_b32_e64 v6, 0, v3, s[38:39]
	v_cndmask_b32_e64 v7, 0, v3, s[40:41]
.LBB0_89:
	s_or_b64 exec, exec, s[10:11]
	s_movk_i32 s20, 0x80
	v_cmp_gt_i32_e64 s[20:21], s20, v182
	s_waitcnt vmcnt(0)
	s_and_saveexec_b64 s[26:27], s[20:21]
	ds_write_b32 v13, v12
	s_mov_b64 exec, s[26:27]
	v_add_u32_e32 v3, 0, v117
	v_add_u32_e32 v3, 0x1ea00, v3
	ds_write_b128 v3, v[4:7]
	v_add_u32_e32 v118, 0x200, v182
	v_mov_b32_e32 v3, 0
	v_mov_b32_e32 v4, 0
	v_mov_b32_e32 v5, 0
	s_and_saveexec_b64 s[10:11], s[42:43]
	s_cbranch_execz .LBB0_91
	v_mov_b32_e32 v0, v11
	v_cvt_pk_bf16_f32 v0, v0, v1
	s_nop 0
	v_lshlrev_b32_sdwa v0, v10, v0 dst_sel:DWORD dst_unused:UNUSED_PAD src0_sel:DWORD src1_sel:WORD_0
	v_cndmask_b32_e32 v2, 0, v0, vcc
	v_cndmask_b32_e64 v3, 0, v0, s[0:1]
	v_cndmask_b32_e64 v4, 0, v0, s[38:39]
	v_cndmask_b32_e64 v5, 0, v0, s[40:41]
.LBB0_91:
	s_or_b64 exec, exec, s[10:11]
	v_and_b32_e32 v0, 63, v182
	s_add_i32 s0, 0, 0x1ea00
	v_lshl_add_u32 v6, v118, 4, s0
	v_lshlrev_b32_e32 v0, 4, v0
	ds_write_b128 v6, v[2:5]
	v_add_u32_e32 v140, 0, v0
	s_waitcnt lgkmcnt(0)
	s_barrier
	v_add_u32_e32 v2, s0, v0
	v_add_u32_e32 v0, 0x1ee00, v140
	ds_read_b128 v[4:7], v2
	ds_read_b128 v[8:11], v0
	v_add_u32_e32 v0, 0x1f200, v140
	ds_read_b128 v[12:15], v0
	v_add_u32_e32 v0, 0x1f600, v140
	ds_read_b128 v[16:19], v0
	v_add_u32_e32 v0, 0x1fa00, v140
	ds_read_b128 v[20:23], v0
	v_add_u32_e32 v0, 0x1fe00, v140
	ds_read_b128 v[24:27], v0
	v_add_u32_e32 v0, 0x20200, v140
	s_lshl_b32 s0, s23, 2
	s_bfe_u32 s28, s22, 0x20003
	ds_read_b128 v[28:31], v0
	v_add_u32_e32 v0, 0x20600, v140
	s_or_b32 s0, s0, s15
	ds_read_b128 v[32:35], v0
	v_add_u32_e32 v0, 0x20a00, v140
	s_or_b32 s0, s0, s28
	ds_read_b128 v[36:39], v0
	v_add_u32_e32 v0, 0x20e00, v140
	s_ashr_i32 s1, s0, 31
	s_lshl_b32 s7, s28, 5
	ds_read_b128 v[40:43], v0
	v_add_u32_e32 v0, 0x21200, v140
	s_lshl_b64 s[0:1], s[0:1], 14
	v_readlane_b32 s10, v253, 9
	ds_read_b128 v[44:47], v0
	v_add_u32_e32 v0, 0x21600, v140
	v_readlane_b32 s11, v253, 10
	s_add_u32 s0, s10, s0
	v_bfe_u32 v213, v182, 4, 2
	ds_read_b128 v[48:51], v0
	s_addc_u32 s1, s11, s1
	v_lshlrev_b32_e32 v0, 8, v141
	v_lshl_add_u64 v[2:3], s[0:1], 0, v[0:1]
	v_lshlrev_b32_e32 v0, 3, v213
	v_lshl_add_u64 v[2:3], v[2:3], 0, v[0:1]
	v_add_co_u32_e32 v82, vcc, 0x1000, v2
	global_load_dwordx2 v[52:53], v[2:3], off
	global_load_dwordx2 v[54:55], v[2:3], off offset:32
	global_load_dwordx2 v[56:57], v[2:3], off offset:64
	global_load_dwordx2 v[58:59], v[2:3], off offset:96
	global_load_dwordx2 v[60:61], v[2:3], off offset:128
	global_load_dwordx2 v[62:63], v[2:3], off offset:160
	global_load_dwordx2 v[64:65], v[2:3], off offset:192
	global_load_dwordx2 v[66:67], v[2:3], off offset:224
	v_addc_co_u32_e32 v83, vcc, 0, v3, vcc
	v_add_co_u32_e32 v98, vcc, 0x2000, v2
	global_load_dwordx2 v[68:69], v[82:83], off
	global_load_dwordx2 v[70:71], v[82:83], off offset:32
	global_load_dwordx2 v[72:73], v[82:83], off offset:64
	global_load_dwordx2 v[74:75], v[82:83], off offset:96
	global_load_dwordx2 v[76:77], v[82:83], off offset:128
	global_load_dwordx2 v[78:79], v[82:83], off offset:160
	global_load_dwordx2 v[80:81], v[82:83], off offset:192
	s_nop 0
	global_load_dwordx2 v[82:83], v[82:83], off offset:224
	v_addc_co_u32_e32 v99, vcc, 0, v3, vcc
	v_add_co_u32_e32 v2, vcc, 0x3000, v2
	global_load_dwordx2 v[84:85], v[98:99], off
	global_load_dwordx2 v[86:87], v[98:99], off offset:32
	global_load_dwordx2 v[88:89], v[98:99], off offset:64
	global_load_dwordx2 v[90:91], v[98:99], off offset:96
	global_load_dwordx2 v[92:93], v[98:99], off offset:128
	global_load_dwordx2 v[94:95], v[98:99], off offset:160
	global_load_dwordx2 v[96:97], v[98:99], off offset:192
	s_nop 0
	global_load_dwordx2 v[98:99], v[98:99], off offset:224
	v_addc_co_u32_e32 v3, vcc, 0, v3, vcc
	global_load_dwordx2 v[100:101], v[2:3], off
	global_load_dwordx2 v[102:103], v[2:3], off offset:32
	global_load_dwordx2 v[104:105], v[2:3], off offset:64
	global_load_dwordx2 v[106:107], v[2:3], off offset:96
	global_load_dwordx2 v[108:109], v[2:3], off offset:128
	global_load_dwordx2 v[110:111], v[2:3], off offset:160
	global_load_dwordx2 v[112:113], v[2:3], off offset:192
	global_load_dwordx2 v[114:115], v[2:3], off offset:224
	s_movk_i32 s0, 0x60
	v_cmp_gt_i32_e32 vcc, s0, v182
	s_and_saveexec_b64 s[10:11], vcc
	s_cbranch_execz .LBB0_105
	v_and_or_b32 v0, v182, 31, s2
	v_or_b32_e32 v0, s6, v0
	v_or_b32_e32 v2, s7, v0
	v_cmp_lt_u32_e32 vcc, 31, v182
	v_ashrrev_i32_e32 v3, 31, v2
	v_mov_b32_e32 v120, s70
	v_mov_b32_e32 v121, s71
	v_mov_b32_e32 v122, s74
	v_mov_b32_e32 v123, s75
	s_movk_i32 s0, 63
	v_cmp_lt_u32_e64 s[0:1], s0, v182
	v_cndmask_b32_e32 v120, v120, v122, vcc
	v_cndmask_b32_e32 v121, v121, v123, vcc
	v_mov_b32_e32 v122, s76
	v_mov_b32_e32 v123, s77
	v_cndmask_b32_e64 v120, v120, v122, s[0:1]
	v_cndmask_b32_e64 v121, v121, v123, s[0:1]
	s_nop 0
	v_lshl_add_u64 v[120:121], v[2:3], 2, v[120:121]
	global_load_dword v124, v[120:121], off
	s_waitcnt vmcnt(0)
	s_and_saveexec_b64 s[0:1], vcc
	s_xor_b64 s[20:21], exec, s[0:1]
	s_cbranch_execz .LBB0_102
	v_and_b32_e32 v0, 0xffffffe0, v182
	v_cmp_ne_u32_e32 vcc, 32, v0
	s_and_saveexec_b64 s[0:1], vcc
	s_xor_b64 s[26:27], exec, s[0:1]
	s_cbranch_execz .LBB0_99
	v_mov_b32_e32 v0, v124
	s_mov_b32 s0, 0xbfb8aa3b
	v_mul_f32_e32 v2, 0xbfb8aa3b, v0
	v_fma_f32 v3, v0, s0, -v2
	v_rndne_f32_e32 v119, v2
	v_fmac_f32_e32 v3, 0xb2a5705f, v0
	v_sub_f32_e32 v2, v2, v119
	v_add_f32_e32 v2, v2, v3
	v_cvt_i32_f32_e32 v119, v119
	v_exp_f32_e32 v2, v2
	s_mov_b32 s0, 0x42ce8ed0
	v_cmp_nlt_f32_e32 vcc, s0, v0
	s_mov_b32 s0, 0xc2b17218
	v_ldexp_f32 v2, v2, v119
	v_cndmask_b32_e32 v2, 0, v2, vcc
	v_cmp_ngt_f32_e32 vcc, s0, v0
	s_mov_b32 s0, 0x3cf5c28f
	s_nop 0
	v_cndmask_b32_e32 v0, v250, v2, vcc
	v_cmp_ngt_f32_e32 vcc, s0, v0
	s_and_saveexec_b64 s[0:1], vcc
	s_xor_b64 s[38:39], exec, s[0:1]
	s_cbranch_execz .LBB0_96
	v_add_f32_e32 v0, 1.0, v0
	s_mov_b32 s0, 0x800000
	v_cmp_gt_f32_e32 vcc, s0, v0
	s_mov_b32 s0, 0x3f317217
	s_nop 0
	v_cndmask_b32_e64 v2, 0, 32, vcc
	v_ldexp_f32 v0, v0, v2
	v_log_f32_e32 v0, v0
	s_nop 0
	v_mul_f32_e32 v2, 0x3f317217, v0
	v_fma_f32 v2, v0, s0, -v2
	v_fmac_f32_e32 v2, 0x3377d1cf, v0
	s_mov_b32 s0, 0x7f800000
	v_fmac_f32_e32 v2, 0x3f317217, v0
	v_cmp_lt_f32_e64 s[0:1], |v0|, s0
	s_nop 1
	v_cndmask_b32_e64 v0, v0, v2, s[0:1]
	v_cndmask_b32_e32 v2, 0, v251, vcc
	v_sub_f32_e32 v2, v0, v2

.LBB0_99:
	s_andn2_saveexec_b64 s[0:1], s[26:27]
	s_cbranch_execz .LBB0_101
	v_mul_f32_e32 v0, 0xbfb8aa3b, v124

.LBB0_102:
	s_andn2_saveexec_b64 s[0:1], s[20:21]
	s_cbranch_execz .LBB0_104
	v_mul_f32_e32 v0, 0xbfb8aa3b, v124

.LBB0_105:
	s_or_b64 exec, exec, s[10:11]
	s_lshl_b32 s0, s22, 7
	s_and_b32 s0, s0, 0xfffff000
	s_ashr_i32 s1, s0, 31
	s_lshl_b64 s[10:11], s[0:1], 11
	s_add_u32 s20, s12, s10
	s_addc_u32 s21, s13, s11
	s_lshl_b32 s6, s6, 1
	s_add_u32 s20, s20, s6
	v_ashrrev_i32_e32 v174, 4, v182
	s_addc_u32 s21, s21, 0
	v_and_b32_e32 v0, 0xf0, v117
	v_ashrrev_i32_e32 v175, 31, v174
	v_lshl_add_u64 v[172:173], s[20:21], 0, v[0:1]
	v_lshlrev_b64 v[2:3], 11, v[174:175]
	s_add_u32 s10, s95, s10
	v_readlane_b32 s26, v253, 39
	v_lshl_add_u64 v[2:3], v[172:173], 0, v[2:3]
	s_addc_u32 s11, s26, s11
	global_load_dwordx4 v[124:127], v[2:3], off
	v_add_u32_e32 v120, 0x600, v182
	s_add_u32 s10, s10, s6
	v_ashrrev_i32_e32 v180, 4, v120
	s_addc_u32 s11, s11, 0
	s_lshl_b32 s7, s7, 1
	v_ashrrev_i32_e32 v168, 2, v182
	v_ashrrev_i32_e32 v176, 4, v118
	v_add_u32_e32 v118, 0x400, v182
	v_ashrrev_i32_e32 v181, 31, v180
	s_add_u32 s26, s10, s7
	v_lshlrev_b32_e32 v122, 3, v182
	v_ashrrev_i32_e32 v178, 4, v118
	v_lshlrev_b64 v[120:121], 11, v[180:181]
	v_ashrrev_i32_e32 v169, 31, v168
	s_addc_u32 s27, s11, 0
	v_ashrrev_i32_e32 v177, 31, v176
	v_ashrrev_i32_e32 v179, 31, v178
	v_lshl_add_u64 v[132:133], v[172:173], 0, v[120:121]
	v_lshlrev_b64 v[120:121], 11, v[168:169]
	v_and_b32_e32 v183, 24, v122
	v_lshlrev_b64 v[116:117], 11, v[176:177]
	v_lshlrev_b64 v[118:119], 11, v[178:179]
	v_lshl_add_u64 v[120:121], s[26:27], 0, v[120:121]
	v_lshlrev_b32_e32 v170, 1, v183
	v_mov_b32_e32 v171, v1
	v_lshl_add_u64 v[116:117], v[172:173], 0, v[116:117]
	v_lshl_add_u64 v[118:119], v[172:173], 0, v[118:119]
	v_lshl_add_u64 v[120:121], v[120:121], 0, v[170:171]
	global_load_dwordx4 v[128:131], v[116:117], off
	global_load_dwordx4 v[134:137], v[118:119], off
	global_load_dwordx4 v[142:145], v[132:133], off
	v_mul_lo_u32 v138, v174, s51
	global_load_dwordx4 v[120:123], v[120:121], off
	v_add_u32_e32 v138, 0, v138
	v_add_u32_e32 v177, v138, v0
	v_lshlrev_b32_e32 v217, 2, v213
	v_cmp_gt_i32_e64 s[38:39], 48, v182
	s_waitcnt vmcnt(0)
	ds_write_b128 v177, v[124:127] offset:816
	v_mul_lo_u32 v124, v176, s51
	v_add_u32_e32 v124, 0, v124
	v_add_u32_e32 v179, v124, v0
	v_mul_lo_u32 v124, v178, s51
	v_add_u32_e32 v124, 0, v124
	v_add_u32_e32 v181, v124, v0
	v_mul_lo_u32 v124, v180, s51
	v_add_u32_e32 v124, 0, v124
	v_add_u32_e32 v199, v124, v0
	ds_write_b128 v179, v[128:131] offset:816
	ds_write_b128 v181, v[134:137] offset:816
	ds_write_b128 v199, v[142:145] offset:816
	s_and_saveexec_b64 s[10:11], s[38:39]
	ds_write_b128 v177, v[234:237]
	s_or_b64 exec, exec, s[10:11]
	v_add_co_u32_e32 v2, vcc, 0x40000, v2
	s_waitcnt lgkmcnt(0)
	s_barrier
	s_nop 0
	v_addc_co_u32_e32 v3, vcc, 0, v3, vcc
	v_add_co_u32_e32 v116, vcc, 0x40000, v116
	v_mov_b32_e32 v0, v1
	s_nop 0
	v_addc_co_u32_e32 v117, vcc, 0, v117, vcc
	global_load_dwordx4 v[124:127], v[2:3], off
	global_load_dwordx4 v[128:131], v[116:117], off
	v_add_co_u32_e32 v2, vcc, 0x40000, v118
	s_nop 1
	v_addc_co_u32_e32 v3, vcc, 0, v119, vcc
	v_add_co_u32_e32 v116, vcc, 0x40000, v132
	s_nop 1
	v_addc_co_u32_e32 v117, vcc, 0, v133, vcc
	global_load_dwordx4 v[132:135], v[2:3], off
	global_load_dwordx4 v[136:139], v[116:117], off
	v_mov_b32_e32 v2, v1
	v_mov_b32_e32 v3, v1
	v_mov_b64_e32 v[118:119], v[2:3]
	v_mov_b64_e32 v[116:117], v[0:1]
	s_and_saveexec_b64 s[10:11], s[38:39]
	s_cbranch_execz .LBB0_109
	v_lshlrev_b64 v[2:3], 11, v[174:175]
	v_lshl_add_u64 v[2:3], v[172:173], 0, v[2:3]
	v_add_co_u32_e32 v2, vcc, 0x3e000, v2
	s_nop 1
	v_addc_co_u32_e32 v3, vcc, 0, v3, vcc
	global_load_dwordx4 v[116:119], v[2:3], off offset:2048
